# layer-0 scan phase: 1000 weight-transpose items shifted from the LRU workgroups (which first run their scan) to the otherwise idle workgroups 224-255
# baseline (speedup 1.0000x reference)
; __device__ __forceinline__ int bid_() { int t = blockIdx.x; asm volatile("" : "+s"(t)); return t; }
; __device__ __forceinline__ void prologue_phase(const Params& P, float* L) {
;     ...
;     for (int it = gw; it < I_ALL; it += NGW) {
;         int r = it;
;         if (r < I_FFN) {
;             const int lf = r / I_LF, q = r % I_LF, which = q / I_F, item = q % I_F;
;             if (which == 0) transpose_item64(P.ffn_w1 + (size_t)lf * DM * FF, DM, FF, W13 + (size_t)lf * NUP * DM, 1, scr, item, lane);
;             else if (which == 1) transpose_item64(P.ffn_w3 + (size_t)lf * DM * FF, DM, FF, W13 + (size_t)lf * NUP * DM, 2, scr, item, lane);
;             else transpose_item64(P.ffn_w2 + (size_t)lf * FF * DM, FF, DM, W2 + (size_t)lf * DM * FF, 0, scr, item, lane);
;         } else {
;             r -= I_FFN;
;             if (r < 2 * I_IN) { const int l = r / I_IN, item = r % I_IN; transpose_item64(P.w_in + (size_t)l * DM * NIN, DM, NIN, WIN + (size_t)l * NINP_W * DM, 3, scr, item, lane); }
;             else { r -= 2 * I_IN; const int l = r / I_OUT, item = r % I_OUT; transpose_item64(P.w_out + (size_t)l * DM * DM, DM, DM, WOUT + (size_t)l * DM * DM, 0, scr, item, lane); }
;         }
;     }
; __device__ __forceinline__ void scan_phase(const Params& P, float* L, int l) {
;     for (int it = bid_(); it < 224; it += gridDim.x) {
;         if (it < 64) scan_hgrn_mfma(P, (unsigned char*)L, l, it);
;         else if (it < 128) scan_ssd_mfma(P, (unsigned char*)L, l, it - 64);
;         else if (it < 192) scan_ret_mfma(P, (unsigned char*)L, it - 128);
;         else scan_lru(P, L, it - 192);
;     }
; }
.Lhk_n1:
	s_cmp_eq_u32 s36, 7
	s_cbranch_scc0 .Lhk_n2
	s_cmp_ge_u32 s2, 192
	s_cbranch_scc0 .Lhk_n2
	s_cmp_lt_u32 s2, 224
	s_cbranch_scc0 .Lhk_n2
	s_mov_b32 s0, 192
	s_mov_b32 s1, 32
	s_mov_b32 s3, 8
	s_mov_b32 s99, 13344
	s_mov_b32 s98, 3000
	s_mov_b32 s100, 0xfffff448
	s_mov_b32 s19, 3000
	s_branch .Lhk_go
.Lhk_n2:
	s_cmp_eq_u32 s36, 7
	s_cbranch_scc0 .Lhk_n3
	s_cmp_ge_u32 s2, 224
	s_cbranch_scc0 .Lhk_n3
	s_cmp_lt_u32 s2, 256
	s_cbranch_scc0 .Lhk_n3
	s_mov_b32 s0, 224
	s_mov_b32 s1, 32
	s_mov_b32 s3, 8
	s_mov_b32 s99, 16344
	s_mov_b32 s98, 9000
	s_mov_b32 s100, 0xffffdcd8
	s_mov_b32 s19, 9000
	s_branch .Lhk_go
